# H1->H2 seam as 4-workgroup flag exchange (per (b,h,dir) group bitmask, placement verified at run time), on v17
# speedup vs baseline: 1.0021x; 1.0021x over previous
.LBB0_328:
	s_cmp_gt_i32 s79, 3
	s_cselect_b64 s[0:1], -1, 0
	s_and_b64 s[2:3], s[40:41], s[0:1]
	s_andn2_b64 vcc, exec, s[2:3]
	s_cbranch_vccnz .LBB0_378
	s_and_b64 vcc, exec, s[92:93]
	s_cbranch_vccz .Lg2_orig
	v_readlane_b32 s4, v246, 1
	v_readlane_b32 s5, v246, 2
	v_mov_b32_e32 v216, 0x3700
	s_nop 4
	global_load_dwordx4 v[200:203], v216, s[4:5] sc1
	global_load_dwordx4 v[204:207], v216, s[4:5] offset:16 sc1
	global_load_dwordx4 v[208:211], v216, s[4:5] offset:256 sc1
	global_load_dwordx4 v[212:215], v216, s[4:5] offset:272 sc1
	s_waitcnt vmcnt(0)
	v_add_u32_e32 v200, v200, v208
	v_xor_b32_e32 v200, 17, v200
	v_add_u32_e32 v201, v201, v209
	v_xor_b32_e32 v201, 17, v201
	v_add_u32_e32 v202, v202, v210
	v_xor_b32_e32 v202, 17, v202
	v_add_u32_e32 v203, v203, v211
	v_xor_b32_e32 v203, 17, v203
	v_add_u32_e32 v204, v204, v212
	v_xor_b32_e32 v204, 17, v204
	v_add_u32_e32 v205, v205, v213
	v_xor_b32_e32 v205, 17, v205
	v_add_u32_e32 v206, v206, v214
	v_xor_b32_e32 v206, 17, v206
	v_add_u32_e32 v207, v207, v215
	v_xor_b32_e32 v207, 17, v207
	v_or3_b32 v200, v200, v201, v202
	v_or3_b32 v203, v203, v204, v205
	v_or3_b32 v200, v200, v206, v207
	v_or_b32_e32 v200, v200, v203
	v_cmp_eq_u32_e32 vcc, 0, v200
	s_nop 1
	s_and_b64 vcc, vcc, exec
	s_cbranch_vccz .Lg2_orig
	s_barrier
	v_cmp_eq_u32_e32 vcc, 0, v171
	s_and_saveexec_b64 s[10:11], vcc
	s_cbranch_execz .Lg2_join
	s_and_b32 s6, s74, 7
	s_lshl_b32 s6, s6, 5
	s_lshr_b32 s7, s74, 3
	s_add_i32 s6, s6, s7
	s_and_b32 s7, s6, 3
	s_lshr_b32 s6, s6, 2
	s_lshl_b32 s6, s6, 6
	s_add_i32 s6, s6, 0xc080
	v_mov_b32_e32 v216, s6
	s_lshl_b32 s8, 1, s7
	v_mov_b32_e32 v217, s8
	s_cmp_eq_u32 s7, 3
	s_cbranch_scc1 .Lg2_np
	global_atomic_or v216, v217, s[4:5]
.Lg2_np:
	s_add_i32 s8, s8, -1
	s_cmp_eq_u32 s8, 0
	s_cbranch_scc1 .Lg2_join
	s_mov_b32 s9, 0
.Lg2_poll:
	global_load_dword v218, v216, s[4:5] sc1
	s_waitcnt vmcnt(0)
	v_readfirstlane_b32 s7, v218
	s_nop 0
	s_and_b32 s7, s7, s8
	s_cmp_eq_u32 s7, s8
	s_cbranch_scc1 .Lg2_ok
	s_sleep 1
	s_add_i32 s9, s9, 1
	s_cmp_lt_u32 s9, 0x40000
	s_cbranch_scc1 .Lg2_poll

.Lg2_join:
	s_or_b64 exec, exec, s[10:11]
	s_barrier
	s_branch .LBB0_378
.Lg2_orig:
	s_waitcnt vmcnt(0)
	v_cmp_eq_u32_e32 vcc, 0, v171
	s_waitcnt vmcnt(0)
	s_barrier
	s_and_saveexec_b64 s[2:3], vcc
	s_cbranch_execz .LBB0_377
	s_add_i32 s4, 0, 0x20000
	v_mov_b32_e32 v0, s4
	s_waitcnt vmcnt(0) expcnt(0) lgkmcnt(0)
	ds_read_b32 v2, v0
	s_add_i32 s4, 0, 0x20004
	v_mov_b32_e32 v0, s4
	ds_read_b32 v0, v0
	s_waitcnt lgkmcnt(1)
	v_cmp_ne_u32_e32 vcc, 0, v2
	s_cbranch_vccnz .LBB0_345
	v_readlane_b32 s4, v246, 0
	s_mul_i32 s33, s53, s4
	s_add_u32 s4, s76, 0x280200
	s_addc_u32 s5, s77, 0
	s_add_u32 s6, s76, 0x280400
	s_addc_u32 s7, s77, 0
	s_add_u32 s8, s76, 0x280500
	s_addc_u32 s9, s77, 0
	s_add_u32 s10, s76, 0x280600
	s_addc_u32 s11, s77, 0
	s_add_u32 s12, s76, 0x280700
	s_addc_u32 s13, s77, 0
	s_add_u32 s14, s76, 0x280800
	s_addc_u32 s15, s77, 0
	s_add_u32 s16, s76, 0x280900
	s_addc_u32 s17, s77, 0
	s_add_u32 s18, s76, 0x280a00
	s_addc_u32 s19, s77, 0
	s_add_u32 s20, s76, 0x280b00
	s_addc_u32 s21, s77, 0
	s_add_u32 s22, s76, 0x280c00
	s_addc_u32 s23, s77, 0
	s_add_u32 s24, s76, 0x280d00
	s_addc_u32 s25, s77, 0
	s_add_u32 s26, s76, 0x280e00
	s_addc_u32 s27, s77, 0
	s_add_u32 s28, s76, 0x280f00
	s_addc_u32 s29, s77, 0
	s_add_u32 s30, s76, 0x281000
	s_addc_u32 s31, s77, 0
	s_add_u32 s34, s76, 0x281100
	s_addc_u32 s35, s77, 0
	s_add_u32 s36, s76, 0x281200
	s_addc_u32 s37, s77, 0
	s_add_u32 s40, s76, 0x281300
	s_mul_i32 s33, s33, s52
	s_addc_u32 s41, s77, 0
	s_mov_b32 s49, 1
	v_mov_b32_e32 v16, 0
	s_branch .LBB0_333
